# v27 + lever 7 in the hand-written attention compute: 36 exp-argument v_fma_f32 -> 18 v_pk_fma_f32 and 32 output-scale v_mul_f32 -> 16 v_pk_mul_f32 (bit-identical)
# baseline (speedup 1.0000x reference)
; __device__ __forceinline__ unsigned pk2(float lo, float hi) { f32x2 v = {lo, hi}; bf2_t b = __builtin_convertvector(v, bf2_t); return __builtin_bit_cast(unsigned, b); }
; __device__ __forceinline__ float shx(float v, int lane, int mask) { return __int_as_float(__builtin_amdgcn_ds_bpermute((lane ^ mask) << 2, __float_as_int(v))); }
; __device__ __forceinline__ void attn_phase(int wv, const Args& a, LAS unsigned char* lds, int w, bool dmy) {
;     ...
;         mx = fmaxf(mx, shx(mx, LANE_, 16)); mx = fmaxf(mx, shx(mx, LANE_, 32));
;         float sum = 0.f;
; #pragma unroll
;         for (int i = 0; i < 10; ++i)
; #pragma unroll
;             for (int rr = 0; rr < 4; ++rr) { const float pv = __expf(sT[i][rr] - mx); sT[i][rr] = pv; sum += pv; }
;         sum += shx(sum, LANE_, 16); sum += shx(sum, LANE_, 32);
;         f32x4 oacc[8];
; #pragma unroll
;         for (int j = 0; j < 8; ++j) oacc[j] = (f32x4){0.f, 0.f, 0.f, 0.f};
; #pragma unroll
;         for (int pp = 0; pp < 5; ++pp) {
;             const int pk0 = (lo2 + 2 * pp) ^ px, pk1 = (lo2 + 2 * pp + 1) ^ px;
;             u32x4 pw; pw.x = pk2(sT[2 * pp][0], sT[2 * pp][1]); pw.y = pk2(sT[2 * pp][2], sT[2 * pp][3]); pw.z = pk2(sT[2 * pp + 1][0], sT[2 * pp + 1][1]); pw.w = pk2(sT[2 * pp + 1][2], sT[2 * pp + 1][3]);
;             const bf16x8 pf = __builtin_bit_cast(bf16x8, pw);
.Lat_n_ok:
	v_max3_f32 v65, v124, v125, v126
	v_max3_f32 v65, v65, v127, v128
	v_max3_f32 v65, v65, v129, v130
	v_max3_f32 v65, v65, v131, v132
	v_max3_f32 v65, v65, v133, v134
	v_max3_f32 v65, v65, v135, v136
	v_max3_f32 v65, v65, v137, v138
	v_max3_f32 v65, v65, v139, v140
	v_max3_f32 v65, v65, v141, v142
	v_max3_f32 v65, v65, v143, v144
	v_max3_f32 v65, v65, v145, v146
	v_max3_f32 v65, v65, v147, v148
	v_max3_f32 v65, v65, v149, v150
	v_max3_f32 v65, v65, v151, v152
	v_max3_f32 v65, v65, v153, v154
	v_max3_f32 v65, v65, v155, v156
	v_max3_f32 v65, v65, v157, v158
	v_max_f32_e32 v65, v65, v159
	ds_bpermute_b32 v67, v97, v65
	s_waitcnt lgkmcnt(0)
	v_max_f32_e32 v65, v65, v67
	ds_bpermute_b32 v67, v104, v65
	s_waitcnt lgkmcnt(0)
	v_max_f32_e32 v65, v65, v67
	v_mul_f32_e32 v101, v65, v66
	v_mul_f32_e32 v65, v65, v64
	v_pk_fma_f32 v[124:125], v[124:125], v[64:65], v[64:65] op_sel:[0,0,1] op_sel_hi:[1,0,1] neg_lo:[0,0,1] neg_hi:[0,0,1]
	v_pk_fma_f32 v[126:127], v[126:127], v[64:65], v[64:65] op_sel:[0,0,1] op_sel_hi:[1,0,1] neg_lo:[0,0,1] neg_hi:[0,0,1]
	v_pk_fma_f32 v[128:129], v[128:129], v[64:65], v[64:65] op_sel:[0,0,1] op_sel_hi:[1,0,1] neg_lo:[0,0,1] neg_hi:[0,0,1]
	v_pk_fma_f32 v[130:131], v[130:131], v[64:65], v[64:65] op_sel:[0,0,1] op_sel_hi:[1,0,1] neg_lo:[0,0,1] neg_hi:[0,0,1]
	v_pk_fma_f32 v[132:133], v[132:133], v[64:65], v[64:65] op_sel:[0,0,1] op_sel_hi:[1,0,1] neg_lo:[0,0,1] neg_hi:[0,0,1]
	v_pk_fma_f32 v[134:135], v[134:135], v[64:65], v[64:65] op_sel:[0,0,1] op_sel_hi:[1,0,1] neg_lo:[0,0,1] neg_hi:[0,0,1]
	v_pk_fma_f32 v[136:137], v[136:137], v[64:65], v[64:65] op_sel:[0,0,1] op_sel_hi:[1,0,1] neg_lo:[0,0,1] neg_hi:[0,0,1]
	v_pk_fma_f32 v[138:139], v[138:139], v[64:65], v[64:65] op_sel:[0,0,1] op_sel_hi:[1,0,1] neg_lo:[0,0,1] neg_hi:[0,0,1]
	v_pk_fma_f32 v[140:141], v[140:141], v[64:65], v[64:65] op_sel:[0,0,1] op_sel_hi:[1,0,1] neg_lo:[0,0,1] neg_hi:[0,0,1]
	v_pk_fma_f32 v[142:143], v[142:143], v[64:65], v[64:65] op_sel:[0,0,1] op_sel_hi:[1,0,1] neg_lo:[0,0,1] neg_hi:[0,0,1]
	v_pk_fma_f32 v[144:145], v[144:145], v[64:65], v[64:65] op_sel:[0,0,1] op_sel_hi:[1,0,1] neg_lo:[0,0,1] neg_hi:[0,0,1]
	v_pk_fma_f32 v[146:147], v[146:147], v[64:65], v[64:65] op_sel:[0,0,1] op_sel_hi:[1,0,1] neg_lo:[0,0,1] neg_hi:[0,0,1]
	v_pk_fma_f32 v[148:149], v[148:149], v[64:65], v[64:65] op_sel:[0,0,1] op_sel_hi:[1,0,1] neg_lo:[0,0,1] neg_hi:[0,0,1]
	v_pk_fma_f32 v[150:151], v[150:151], v[64:65], v[64:65] op_sel:[0,0,1] op_sel_hi:[1,0,1] neg_lo:[0,0,1] neg_hi:[0,0,1]
	v_pk_fma_f32 v[152:153], v[152:153], v[64:65], v[64:65] op_sel:[0,0,1] op_sel_hi:[1,0,1] neg_lo:[0,0,1] neg_hi:[0,0,1]
	v_pk_fma_f32 v[154:155], v[154:155], v[64:65], v[64:65] op_sel:[0,0,1] op_sel_hi:[1,0,1] neg_lo:[0,0,1] neg_hi:[0,0,1]
	v_pk_fma_f32 v[156:157], v[156:157], v[64:65], v[64:65] op_sel:[0,0,1] op_sel_hi:[1,0,1] neg_lo:[0,0,1] neg_hi:[0,0,1]
	v_pk_fma_f32 v[158:159], v[158:159], v[64:65], v[64:65] op_sel:[0,0,1] op_sel_hi:[1,0,1] neg_lo:[0,0,1] neg_hi:[0,0,1]
	v_exp_f32_e32 v124, v124
	v_exp_f32_e32 v125, v125
	v_exp_f32_e32 v126, v126
	v_add_f32_e32 v103, v124, v125
	v_exp_f32_e32 v127, v127
	v_add_f32_e32 v103, v103, v126
	v_exp_f32_e32 v128, v128
	v_add_f32_e32 v103, v103, v127
	v_exp_f32_e32 v129, v129
	v_add_f32_e32 v103, v103, v128
	v_exp_f32_e32 v130, v130
	v_add_f32_e32 v103, v103, v129
	v_exp_f32_e32 v131, v131
	v_add_f32_e32 v103, v103, v130
	v_exp_f32_e32 v132, v132
	v_add_f32_e32 v103, v103, v131
	v_exp_f32_e32 v133, v133
	v_add_f32_e32 v103, v103, v132
	v_exp_f32_e32 v134, v134
	v_add_f32_e32 v103, v103, v133
	v_exp_f32_e32 v135, v135
	v_add_f32_e32 v103, v103, v134
	v_exp_f32_e32 v136, v136
	v_add_f32_e32 v103, v103, v135
	v_exp_f32_e32 v137, v137
	v_add_f32_e32 v103, v103, v136
	v_exp_f32_e32 v138, v138
	v_add_f32_e32 v103, v103, v137
	v_exp_f32_e32 v139, v139
	v_add_f32_e32 v103, v103, v138
	v_exp_f32_e32 v140, v140
	v_add_f32_e32 v103, v103, v139
	v_exp_f32_e32 v141, v141
	v_add_f32_e32 v103, v103, v140
	v_exp_f32_e32 v142, v142
	v_add_f32_e32 v103, v103, v141
	v_exp_f32_e32 v143, v143
	v_add_f32_e32 v103, v103, v142
	v_exp_f32_e32 v144, v144
	v_add_f32_e32 v103, v103, v143
	v_exp_f32_e32 v145, v145
	v_add_f32_e32 v103, v103, v144
	v_exp_f32_e32 v146, v146
	v_add_f32_e32 v103, v103, v145
	v_exp_f32_e32 v147, v147
	v_add_f32_e32 v103, v103, v146
	v_exp_f32_e32 v148, v148
	v_add_f32_e32 v103, v103, v147
	v_exp_f32_e32 v149, v149
	v_add_f32_e32 v103, v103, v148
	v_exp_f32_e32 v150, v150
	v_add_f32_e32 v103, v103, v149
	v_exp_f32_e32 v151, v151
	v_add_f32_e32 v103, v103, v150
	v_exp_f32_e32 v152, v152
	v_add_f32_e32 v103, v103, v151
	v_exp_f32_e32 v153, v153
	v_add_f32_e32 v103, v103, v152
	v_exp_f32_e32 v154, v154
	v_add_f32_e32 v103, v103, v153
	v_exp_f32_e32 v155, v155
	v_add_f32_e32 v103, v103, v154
	v_exp_f32_e32 v156, v156
	v_add_f32_e32 v103, v103, v155
	v_exp_f32_e32 v157, v157
	v_add_f32_e32 v103, v103, v156
	v_exp_f32_e32 v158, v158
	v_add_f32_e32 v103, v103, v157
	v_exp_f32_e32 v159, v159
	v_add_f32_e32 v103, v103, v158
	s_nop 0
	v_add_f32_e32 v103, v103, v159
	ds_bpermute_b32 v67, v97, v103
	v_cvt_pk_bf16_f32 v166, v124, v125
	v_cvt_pk_bf16_f32 v167, v126, v127
	v_cvt_pk_bf16_f32 v168, v128, v129
	v_cvt_pk_bf16_f32 v169, v130, v131
	v_cvt_pk_bf16_f32 v170, v132, v133
	v_cvt_pk_bf16_f32 v171, v134, v135
	v_cvt_pk_bf16_f32 v172, v136, v137
	v_cvt_pk_bf16_f32 v173, v138, v139
	v_cvt_pk_bf16_f32 v174, v140, v141
	v_cvt_pk_bf16_f32 v175, v142, v143
	v_cvt_pk_bf16_f32 v176, v144, v145
	v_cvt_pk_bf16_f32 v177, v146, v147
	v_cvt_pk_bf16_f32 v178, v148, v149
	v_cvt_pk_bf16_f32 v179, v150, v151
	v_cvt_pk_bf16_f32 v180, v152, v153
	v_cvt_pk_bf16_f32 v181, v154, v155
	v_cvt_pk_bf16_f32 v198, v156, v157
	v_cvt_pk_bf16_f32 v199, v158, v159
	v_mov_b32_e32 v200, 0
	v_mov_b32_e32 v201, 0
	s_waitcnt lgkmcnt(0)
; #define LAS __attribute__((address_space(3)))
; __device__ __forceinline__ float shx(float v, int lane, int mask) { return __int_as_float(__builtin_amdgcn_ds_bpermute((lane ^ mask) << 2, __float_as_int(v))); }
; __device__ __forceinline__ f32x4 mfma16(bf16x8 a, bf16x8 b, f32x4 c) { return __builtin_amdgcn_mfma_f32_16x16x32_bf16(a, b, c, 0, 0, 0); }
; __device__ __forceinline__ void attn_phase(int wv, const Args& a, LAS unsigned char* lds, int w, bool dmy) {
;     ...
;         sum += shx(sum, LANE_, 16); sum += shx(sum, LANE_, 32);
;     ...
; #pragma unroll
;             for (int j = 0; j < 8; ++j) {
;                 const u32x2 v0 = *(const LAS u32x2*)(lds + AT_V + ((j * 16 + fr) * 264 + pk0 * 16 + 4 * fq) * 2);
;                 const u32x2 v1 = *(const LAS u32x2*)(lds + AT_V + ((j * 16 + fr) * 264 + pk1 * 16 + 4 * fq) * 2);
;                 const u32x4 vw = (u32x4){v0.x, v0.y, v1.x, v1.y};
;                 oacc[j] = mfma16(__builtin_bit_cast(bf16x8, vw), pf, oacc[j]);
;             }
;         }
	v_add_f32_e32 v103, v103, v67
	ds_bpermute_b32 v67, v104, v103
	s_waitcnt lgkmcnt(0)
	v_add_f32_e32 v81, v103, v67
	ds_read_b64 v[48:49], v182
	ds_read_b64 v[50:51], v183
	ds_read_b64 v[52:53], v182 offset:8448
	ds_read_b64 v[54:55], v183 offset:8448
	ds_read_b64 v[56:57], v182 offset:16896
	ds_read_b64 v[58:59], v183 offset:16896
	ds_read_b64 v[60:61], v182 offset:25344
	ds_read_b64 v[62:63], v183 offset:25344
	ds_read_b64 v[64:65], v182 offset:33792
	ds_read_b64 v[66:67], v183 offset:33792
	ds_read_b64 v[68:69], v182 offset:42240
	ds_read_b64 v[70:71], v183 offset:42240
	ds_read_b64 v[72:73], v182 offset:50688
	ds_read_b64 v[74:75], v183 offset:50688
	ds_read_b64 v[76:77], v182 offset:59136
	s_waitcnt lgkmcnt(14)
	ds_read_b64 v[78:79], v183 offset:59136
	s_waitcnt lgkmcnt(8)
	v_mfma_f32_16x16x32_bf16 v[124:127], v[48:51], v[166:169], 0
	v_mfma_f32_16x16x32_bf16 v[128:131], v[52:55], v[166:169], 0
	v_mfma_f32_16x16x32_bf16 v[132:135], v[56:59], v[166:169], 0
	v_mfma_f32_16x16x32_bf16 v[136:139], v[60:63], v[166:169], 0
	ds_read_b64 v[48:49], v184
	ds_read_b64 v[50:51], v185
	ds_read_b64 v[52:53], v184 offset:8448
	ds_read_b64 v[54:55], v185 offset:8448
	ds_read_b64 v[56:57], v184 offset:16896
	ds_read_b64 v[58:59], v185 offset:16896
	ds_read_b64 v[60:61], v184 offset:25344
	s_waitcnt lgkmcnt(14)
	ds_read_b64 v[62:63], v185 offset:25344
	s_waitcnt lgkmcnt(8)
	v_mfma_f32_16x16x32_bf16 v[140:143], v[64:67], v[166:169], 0
	v_mfma_f32_16x16x32_bf16 v[144:147], v[68:71], v[166:169], 0
	v_mfma_f32_16x16x32_bf16 v[148:151], v[72:75], v[166:169], 0
	v_mfma_f32_16x16x32_bf16 v[152:155], v[76:79], v[166:169], 0
	ds_read_b64 v[64:65], v184 offset:33792
	ds_read_b64 v[66:67], v185 offset:33792
	ds_read_b64 v[68:69], v184 offset:42240
	ds_read_b64 v[70:71], v185 offset:42240
	ds_read_b64 v[72:73], v184 offset:50688
	ds_read_b64 v[74:75], v185 offset:50688
	ds_read_b64 v[76:77], v184 offset:59136
	s_waitcnt lgkmcnt(14)
	ds_read_b64 v[78:79], v185 offset:59136
	s_waitcnt lgkmcnt(8)
	v_mfma_f32_16x16x32_bf16 v[124:127], v[48:51], v[170:173], v[124:127]
	v_mfma_f32_16x16x32_bf16 v[128:131], v[52:55], v[170:173], v[128:131]
	v_mfma_f32_16x16x32_bf16 v[132:135], v[56:59], v[170:173], v[132:135]
	v_mfma_f32_16x16x32_bf16 v[136:139], v[60:63], v[170:173], v[136:139]
	ds_read_b64 v[48:49], v186
	ds_read_b64 v[50:51], v187
	ds_read_b64 v[52:53], v186 offset:8448
	ds_read_b64 v[54:55], v187 offset:8448
	ds_read_b64 v[56:57], v186 offset:16896
	ds_read_b64 v[58:59], v187 offset:16896
	ds_read_b64 v[60:61], v186 offset:25344
	s_waitcnt lgkmcnt(14)
	ds_read_b64 v[62:63], v187 offset:25344
	s_waitcnt lgkmcnt(8)
	v_mfma_f32_16x16x32_bf16 v[140:143], v[64:67], v[170:173], v[140:143]
	v_mfma_f32_16x16x32_bf16 v[144:147], v[68:71], v[170:173], v[144:147]
	v_mfma_f32_16x16x32_bf16 v[148:151], v[72:75], v[170:173], v[148:151]
	v_mfma_f32_16x16x32_bf16 v[152:155], v[76:79], v[170:173], v[152:155]
	ds_read_b64 v[64:65], v186 offset:33792
	ds_read_b64 v[66:67], v187 offset:33792
	ds_read_b64 v[68:69], v186 offset:42240
	ds_read_b64 v[70:71], v187 offset:42240
	ds_read_b64 v[72:73], v186 offset:50688
	ds_read_b64 v[74:75], v187 offset:50688
	ds_read_b64 v[76:77], v186 offset:59136
	s_waitcnt lgkmcnt(14)
	ds_read_b64 v[78:79], v187 offset:59136
	s_waitcnt lgkmcnt(8)
	v_mfma_f32_16x16x32_bf16 v[124:127], v[48:51], v[174:177], v[124:127]
	v_mfma_f32_16x16x32_bf16 v[128:131], v[52:55], v[174:177], v[128:131]
	v_mfma_f32_16x16x32_bf16 v[132:135], v[56:59], v[174:177], v[132:135]
	v_mfma_f32_16x16x32_bf16 v[136:139], v[60:63], v[174:177], v[136:139]
	ds_read_b64 v[48:49], v227
	ds_read_b64 v[50:51], v228
	ds_read_b64 v[52:53], v227 offset:8448
	ds_read_b64 v[54:55], v228 offset:8448
	ds_read_b64 v[56:57], v227 offset:16896
	ds_read_b64 v[58:59], v228 offset:16896
	ds_read_b64 v[60:61], v227 offset:25344
	s_waitcnt lgkmcnt(14)
	ds_read_b64 v[62:63], v228 offset:25344
	s_waitcnt lgkmcnt(8)
	v_mfma_f32_16x16x32_bf16 v[140:143], v[64:67], v[174:177], v[140:143]
	v_mfma_f32_16x16x32_bf16 v[144:147], v[68:71], v[174:177], v[144:147]
	v_mfma_f32_16x16x32_bf16 v[148:151], v[72:75], v[174:177], v[148:151]
	v_mfma_f32_16x16x32_bf16 v[152:155], v[76:79], v[174:177], v[152:155]
	ds_read_b64 v[64:65], v227 offset:33792
	ds_read_b64 v[66:67], v228 offset:33792
	ds_read_b64 v[68:69], v227 offset:42240
	ds_read_b64 v[70:71], v228 offset:42240
	ds_read_b64 v[72:73], v227 offset:50688
	ds_read_b64 v[74:75], v228 offset:50688
	ds_read_b64 v[76:77], v227 offset:59136
	s_waitcnt lgkmcnt(14)
	ds_read_b64 v[78:79], v228 offset:59136
	s_waitcnt lgkmcnt(8)
	v_mfma_f32_16x16x32_bf16 v[124:127], v[48:51], v[178:181], v[124:127]
	v_mfma_f32_16x16x32_bf16 v[128:131], v[52:55], v[178:181], v[128:131]
	v_mfma_f32_16x16x32_bf16 v[132:135], v[56:59], v[178:181], v[132:135]
	v_mfma_f32_16x16x32_bf16 v[136:139], v[60:63], v[178:181], v[136:139]
	ds_read_b64 v[48:49], v234
	ds_read_b64 v[50:51], v234
	ds_read_b64 v[52:53], v234 offset:8448
	ds_read_b64 v[54:55], v234 offset:8448
	ds_read_b64 v[56:57], v234 offset:16896
	ds_read_b64 v[58:59], v234 offset:16896
	ds_read_b64 v[60:61], v234 offset:25344
	s_waitcnt lgkmcnt(14)
	ds_read_b64 v[62:63], v234 offset:25344
	s_waitcnt lgkmcnt(8)
; __device__ __forceinline__ unsigned pk2(float lo, float hi) { f32x2 v = {lo, hi}; bf2_t b = __builtin_convertvector(v, bf2_t); return __builtin_bit_cast(unsigned, b); }
; __device__ __forceinline__ void attn_phase(int wv, const Args& a, LAS unsigned char* lds, int w, bool dmy) {
;     ...
;         const float inv = 1.f / sum;
; #pragma unroll
;         for (int j = 0; j < 8; ++j) { u32x2 wv; wv.x = pk2(oacc[j][0] * inv, oacc[j][1] * inv); wv.y = pk2(oacc[j][2] * inv, oacc[j][3] * inv);
;             *(u32x2*)((dmy ? (bf16_t*)(a.ws + WS_DUMMY) + (size_t)qi * ATW : AQ + tokq * ATW) + head * 128 + j * 16 + 4 * fq) = wv; }
;         if (fq == 0) (dmy ? (float*)(a.ws + WS_DUMMY + MiB) + qi * 12 : LSE + tokq * 12)[head] = mx + __logf(sum);
	v_mfma_f32_16x16x32_bf16 v[140:143], v[64:67], v[178:181], v[140:143]
	v_mfma_f32_16x16x32_bf16 v[144:147], v[68:71], v[178:181], v[144:147]
	v_mfma_f32_16x16x32_bf16 v[148:151], v[72:75], v[178:181], v[148:151]
	v_mfma_f32_16x16x32_bf16 v[152:155], v[76:79], v[178:181], v[152:155]
	ds_read_b64 v[64:65], v234 offset:33792
	ds_read_b64 v[66:67], v234 offset:33792
	ds_read_b64 v[68:69], v234 offset:42240
	ds_read_b64 v[70:71], v234 offset:42240
	ds_read_b64 v[72:73], v234 offset:50688
	ds_read_b64 v[74:75], v234 offset:50688
	ds_read_b64 v[76:77], v234 offset:59136
	s_waitcnt lgkmcnt(14)
	ds_read_b64 v[78:79], v234 offset:59136
	v_div_scale_f32 v80, s[2:3], v81, v81, 1.0
	v_div_scale_f32 v83, vcc, 1.0, v81, 1.0
	v_rcp_f32_e32 v82, v80
	s_nop 0
	v_fma_f32 v164, -v80, v82, 1.0
	v_fmac_f32_e32 v82, v164, v82
	v_mul_f32_e32 v103, v83, v82
	v_fma_f32 v164, -v80, v103, v83
	v_fmac_f32_e32 v103, v164, v82
	v_fma_f32 v80, -v80, v103, v83
	v_div_fmas_f32 v80, v80, v82, v103
	v_div_fixup_f32 v80, v80, v81, 1.0
	s_waitcnt lgkmcnt(8)
	v_mfma_f32_16x16x32_bf16 v[124:127], v[48:51], v[198:201], v[124:127]
	v_mfma_f32_16x16x32_bf16 v[128:131], v[52:55], v[198:201], v[128:131]
	v_mfma_f32_16x16x32_bf16 v[132:135], v[56:59], v[198:201], v[132:135]
	v_mfma_f32_16x16x32_bf16 v[136:139], v[60:63], v[198:201], v[136:139]
	s_waitcnt lgkmcnt(0)
	v_mfma_f32_16x16x32_bf16 v[140:143], v[64:67], v[198:201], v[140:143]
	v_mfma_f32_16x16x32_bf16 v[144:147], v[68:71], v[198:201], v[144:147]
	v_mfma_f32_16x16x32_bf16 v[148:151], v[72:75], v[198:201], v[148:151]
	v_mfma_f32_16x16x32_bf16 v[152:155], v[76:79], v[198:201], v[152:155]
	s_movk_i32 s2, 0xc00
	v_mov_b64_e32 v[82:83], s[78:79]
	v_mad_u64_u32 v[82:83], s[0:1], v102, s2, v[82:83]
	v_mov_b32_e32 v164, v83
	v_mov_b32_e32 v165, v189
	v_mad_u64_u32 v[164:165], s[0:1], v100, s2, v[164:165]
	s_lshl_b32 s0, s80, 7
	v_mov_b32_e32 v83, v164
	s_ashr_i32 s1, s0, 31
	v_lshl_add_u64 v[82:83], s[0:1], 1, v[82:83]
	v_lshlrev_b32_e32 v188, 1, v88
	s_nop 1
	v_lshl_add_u64 v[82:83], v[82:83], 0, v[188:189]
	v_and_b32_e32 v166, 8, v188
	v_mov_b32_e32 v167, 0
	v_lshl_add_u32 v166, v166, 1, v166
	v_lshl_add_u64 v[82:83], v[166:167], 0, v[82:83]
	v_pk_mul_f32 v[124:125], v[124:125], v[80:81] op_sel_hi:[1,0]
	v_pk_mul_f32 v[126:127], v[126:127], v[80:81] op_sel_hi:[1,0]
	v_pk_mul_f32 v[128:129], v[128:129], v[80:81] op_sel_hi:[1,0]
	v_pk_mul_f32 v[130:131], v[130:131], v[80:81] op_sel_hi:[1,0]
	v_pk_mul_f32 v[132:133], v[132:133], v[80:81] op_sel_hi:[1,0]
	v_pk_mul_f32 v[134:135], v[134:135], v[80:81] op_sel_hi:[1,0]
	v_pk_mul_f32 v[136:137], v[136:137], v[80:81] op_sel_hi:[1,0]
	v_pk_mul_f32 v[138:139], v[138:139], v[80:81] op_sel_hi:[1,0]
	v_pk_mul_f32 v[140:141], v[140:141], v[80:81] op_sel_hi:[1,0]
	v_pk_mul_f32 v[142:143], v[142:143], v[80:81] op_sel_hi:[1,0]
	v_pk_mul_f32 v[144:145], v[144:145], v[80:81] op_sel_hi:[1,0]
	v_pk_mul_f32 v[146:147], v[146:147], v[80:81] op_sel_hi:[1,0]
	v_pk_mul_f32 v[148:149], v[148:149], v[80:81] op_sel_hi:[1,0]
	v_pk_mul_f32 v[150:151], v[150:151], v[80:81] op_sel_hi:[1,0]
	v_pk_mul_f32 v[152:153], v[152:153], v[80:81] op_sel_hi:[1,0]
	v_pk_mul_f32 v[154:155], v[154:155], v[80:81] op_sel_hi:[1,0]
	v_cvt_pk_bf16_f32 v48, v124, v125
	v_cvt_pk_bf16_f32 v49, v126, v127
	v_cvt_pk_bf16_f32 v50, v128, v129
	v_cvt_pk_bf16_f32 v51, v130, v131
	v_cvt_pk_bf16_f32 v52, v132, v133
	v_cvt_pk_bf16_f32 v53, v134, v135
	v_cvt_pk_bf16_f32 v54, v136, v137
	v_cvt_pk_bf16_f32 v55, v138, v139
	v_cvt_pk_bf16_f32 v56, v140, v141
	v_cvt_pk_bf16_f32 v57, v142, v143
	v_cvt_pk_bf16_f32 v58, v144, v145
	v_cvt_pk_bf16_f32 v59, v146, v147
	v_cvt_pk_bf16_f32 v60, v148, v149
	v_cvt_pk_bf16_f32 v61, v150, v151
	v_cvt_pk_bf16_f32 v62, v152, v153
	v_cvt_pk_bf16_f32 v63, v154, v155
	s_nop 1
	v_permlane16_swap_b32_e32 v48, v50
	v_permlane16_swap_b32_e32 v49, v51
	v_permlane16_swap_b32_e32 v52, v54
	v_permlane16_swap_b32_e32 v53, v55
	v_permlane16_swap_b32_e32 v56, v58
	v_permlane16_swap_b32_e32 v57, v59
	v_permlane16_swap_b32_e32 v60, v62
	v_permlane16_swap_b32_e32 v61, v63
	global_store_dwordx4 v[82:83], v[48:51], off
	global_store_dwordx4 v[82:83], v[52:55], off offset:64
	global_store_dwordx4 v[82:83], v[56:59], off offset:128
	global_store_dwordx4 v[82:83], v[60:63], off offset:192
	s_mov_b64 s[86:87], exec
	v_readlane_b32 s0, v255, 3
	v_readlane_b32 s1, v255, 4
	s_and_b64 s[0:1], s[86:87], s[0:1]
	s_mov_b64 exec, s[0:1]
	s_cbranch_execz .LBB0_652
	v_cmp_gt_f32_e32 vcc, s33, v81
	v_readlane_b32 s0, v253, 38
	v_readlane_b32 s1, v253, 39
	v_cndmask_b32_e64 v48, 0, 32, vcc
	v_ldexp_f32 v48, v81, v48
	v_log_f32_e32 v48, v48
	v_cndmask_b32_e32 v49, 0, v237, vcc
	s_ashr_i32 s81, s80, 31
	v_mul_f32_e32 v50, 0x3f317217, v48
	v_fma_f32 v50, v48, s93, -v50
	v_fmac_f32_e32 v50, 0x3377d1cf, v48
	v_fmac_f32_e32 v50, 0x3f317217, v48
	v_cmp_lt_f32_e64 vcc, |v48|, s92
	s_nop 1
	v_cndmask_b32_e32 v48, v48, v50, vcc
	v_sub_f32_e32 v48, v48, v49
	v_add_f32_e32 v52, v101, v48
	v_mad_u64_u32 v[48:49], s[0:1], v102, 48, s[0:1]
	v_mov_b32_e32 v50, v49
	v_mad_u64_u32 v[50:51], s[0:1], v100, 48, v[50:51]
	v_mov_b32_e32 v49, v50
	v_lshl_add_u64 v[48:49], s[80:81], 2, v[48:49]
	global_store_dword v[48:49], v52, off
	s_branch .LBB0_652
